# grid barrier: non-leader blocks poll the top-level generation word directly instead of waiting for their XCD leader to republish it
# speedup vs baseline: 1.0065x; 1.0065x over previous
; DI unsigned xb_ld(unsigned* p) { return __hip_atomic_load(p, __ATOMIC_RELAXED, __HIP_MEMORY_SCOPE_AGENT); }
; DI unsigned xb_add(unsigned* p, unsigned v) { return __hip_atomic_fetch_add(p, v, __ATOMIC_RELAXED, __HIP_MEMORY_SCOPE_AGENT); }
; #define XB_SPIN(cond, bar) do { unsigned _sp = 0; while (cond) { __builtin_amdgcn_s_sleep(1); \
;     if ((++_sp & 255u) == 0u) { if (xb_ld(&(bar)[XB_TMO])) break; if (_sp > XB_SPIN_CAP) { atomicAdd(&(bar)[XB_TMO], 1u); break; } } } } while (0)
; DI void xcd_barrier(const XcdBarrier& b) {
;     ...
;         const unsigned old = xb_add(&bar[XB_XSUB(b.x)], 1u);
;         const unsigned gen = old / nloc;
;         if (old + 1u == (gen + 1u) * nloc) {
;             __builtin_amdgcn_fence(__ATOMIC_RELEASE, "agent");
;             asm volatile("s_waitcnt vmcnt(0)" ::: "memory");
;             const unsigned og = xb_add(&bar[XB_TOP], 1u);
;             const unsigned tg = og / nx;
;             if (og + 1u == (tg + 1u) * nx) xb_add(&bar[XB_TOPGEN], 1u);
;             else XB_SPIN(xb_ld(&bar[XB_TOPGEN]) == tg, bar);
;             __builtin_amdgcn_fence(__ATOMIC_ACQUIRE, "agent");
;             xb_add(&bar[XB_XGEN(b.x)], 1u);
;             asm volatile("s_waitcnt vmcnt(0)" ::: "memory");
;         } else {
;             XB_SPIN(xb_ld(&bar[XB_XGEN(b.x)]) == gen, bar);
;             __builtin_amdgcn_fence(__ATOMIC_ACQUIRE, "agent");
;             asm volatile("s_waitcnt vmcnt(0)" ::: "memory");
;         }
.LBB0_146:
	v_readlane_b32 s2, v238, 14
	s_lshl_b32 s2, s2, 8
	v_readlane_b32 s4, v238, 12
	v_readlane_b32 s5, v238, 13
	s_add_u32 s2, s4, s2
	s_addc_u32 s3, s5, 0
	v_mov_b32_e32 v2, 0x1000
	v_mov_b32_e32 v4, 1
	global_atomic_add v4, v2, v4, s[2:3] offset:1024 sc0
	v_cvt_f32_u32_e32 v2, v3
	v_sub_u32_e32 v5, 0, v3
	v_rcp_iflag_f32_e32 v2, v2
	s_nop 0
	v_mul_f32_e32 v2, 0x4f7ffffe, v2
	v_cvt_u32_f32_e32 v2, v2
	v_mul_lo_u32 v5, v5, v2
	v_mul_hi_u32 v5, v2, v5
	v_add_u32_e32 v2, v2, v5
	s_waitcnt vmcnt(0)
	v_mul_hi_u32 v2, v4, v2
	v_mul_lo_u32 v5, v2, v3
	v_sub_u32_e32 v5, v4, v5
	v_add_u32_e32 v6, 1, v2
	v_cmp_ge_u32_e32 vcc, v5, v3
	v_add_u32_e32 v4, 1, v4
	s_nop 0
	v_cndmask_b32_e32 v2, v2, v6, vcc
	v_sub_u32_e32 v6, v5, v3
	v_cndmask_b32_e32 v5, v5, v6, vcc
	v_add_u32_e32 v6, 1, v2
	v_cmp_ge_u32_e32 vcc, v5, v3
	s_nop 1
	v_cndmask_b32_e32 v2, v2, v6, vcc
	v_mul_lo_u32 v5, v3, v2
	v_add_u32_e32 v3, v5, v3
	v_cmp_ne_u32_e32 vcc, v4, v3
	s_and_saveexec_b64 s[4:5], vcc
	s_xor_b64 s[4:5], exec, s[4:5]
	s_cbranch_execz .LBB0_160
	s_waitcnt lgkmcnt(0)
	v_mov_b32_e32 v1, 0x4000
	global_load_dword v1, v1, s[88:89] offset:1280 sc1
	s_add_u32 s10, s88, 0x4500
	s_addc_u32 s11, s89, 0
	s_waitcnt vmcnt(0)
	v_cmp_eq_u32_e32 vcc, v1, v2
	s_and_saveexec_b64 s[6:7], vcc
	s_cbranch_execz .LBB0_159
	s_add_u32 s8, s88, 0x1200
	s_addc_u32 s9, s89, 0
	s_mov_b32 s22, 1
	s_mov_b64 s[12:13], 0
	v_mov_b32_e32 v1, 0
	s_branch .LBB0_150

; DI unsigned xb_ld(unsigned* p) { return __hip_atomic_load(p, __ATOMIC_RELAXED, __HIP_MEMORY_SCOPE_AGENT); }
; DI unsigned xb_add(unsigned* p, unsigned v) { return __hip_atomic_fetch_add(p, v, __ATOMIC_RELAXED, __HIP_MEMORY_SCOPE_AGENT); }
; #define XB_SPIN(cond, bar) do { unsigned _sp = 0; while (cond) { __builtin_amdgcn_s_sleep(1); \
;     if ((++_sp & 255u) == 0u) { if (xb_ld(&(bar)[XB_TMO])) break; if (_sp > XB_SPIN_CAP) { atomicAdd(&(bar)[XB_TMO], 1u); break; } } } } while (0)
; DI void xcd_barrier(const XcdBarrier& b) {
;     ...
;         const unsigned old = xb_add(&bar[XB_XSUB(b.x)], 1u);
;         const unsigned gen = old / nloc;
;         if (old + 1u == (gen + 1u) * nloc) {
;             __builtin_amdgcn_fence(__ATOMIC_RELEASE, "agent");
;             asm volatile("s_waitcnt vmcnt(0)" ::: "memory");
;             const unsigned og = xb_add(&bar[XB_TOP], 1u);
;             const unsigned tg = og / nx;
;             if (og + 1u == (tg + 1u) * nx) xb_add(&bar[XB_TOPGEN], 1u);
;             else XB_SPIN(xb_ld(&bar[XB_TOPGEN]) == tg, bar);
;             __builtin_amdgcn_fence(__ATOMIC_ACQUIRE, "agent");
;             xb_add(&bar[XB_XGEN(b.x)], 1u);
;             asm volatile("s_waitcnt vmcnt(0)" ::: "memory");
;         } else {
;             XB_SPIN(xb_ld(&bar[XB_XGEN(b.x)]) == gen, bar);
;             __builtin_amdgcn_fence(__ATOMIC_ACQUIRE, "agent");
;             asm volatile("s_waitcnt vmcnt(0)" ::: "memory");
;         }
.LBB0_594:
	v_readlane_b32 s0, v238, 14
	s_lshl_b32 s0, s0, 8
	v_readlane_b32 s4, v238, 12
	v_readlane_b32 s5, v238, 13
	s_add_u32 s0, s4, s0
	s_addc_u32 s1, s5, 0
	v_mov_b32_e32 v2, 0x1000
	v_mov_b32_e32 v4, 1
	global_atomic_add v4, v2, v4, s[0:1] offset:1024 sc0
	v_cvt_f32_u32_e32 v2, v3
	v_sub_u32_e32 v5, 0, v3
	v_rcp_iflag_f32_e32 v2, v2
	s_nop 0
	v_mul_f32_e32 v2, 0x4f7ffffe, v2
	v_cvt_u32_f32_e32 v2, v2
	v_mul_lo_u32 v5, v5, v2
	v_mul_hi_u32 v5, v2, v5
	v_add_u32_e32 v2, v2, v5
	s_waitcnt vmcnt(0)
	v_mul_hi_u32 v2, v4, v2
	v_mul_lo_u32 v5, v2, v3
	v_sub_u32_e32 v5, v4, v5
	v_add_u32_e32 v6, 1, v2
	v_cmp_ge_u32_e32 vcc, v5, v3
	v_add_u32_e32 v4, 1, v4
	s_nop 0
	v_cndmask_b32_e32 v2, v2, v6, vcc
	v_sub_u32_e32 v6, v5, v3
	v_cndmask_b32_e32 v5, v5, v6, vcc
	v_add_u32_e32 v6, 1, v2
	v_cmp_ge_u32_e32 vcc, v5, v3
	s_nop 1
	v_cndmask_b32_e32 v2, v2, v6, vcc
	v_mul_lo_u32 v5, v3, v2
	v_add_u32_e32 v3, v5, v3
	v_cmp_ne_u32_e32 vcc, v4, v3
	s_and_saveexec_b64 s[4:5], vcc
	s_xor_b64 s[4:5], exec, s[4:5]
	s_cbranch_execz .LBB0_608
	s_waitcnt lgkmcnt(0)
	v_mov_b32_e32 v1, 0x4000
	global_load_dword v1, v1, s[88:89] offset:1280 sc1
	s_add_u32 s10, s88, 0x4500
	s_addc_u32 s11, s89, 0
	s_waitcnt vmcnt(0)
	v_cmp_eq_u32_e32 vcc, v1, v2
	s_and_saveexec_b64 s[6:7], vcc
	s_cbranch_execz .LBB0_607
	s_add_u32 s8, s88, 0x1200
	s_addc_u32 s9, s89, 0
	s_mov_b32 s22, 1
	s_mov_b64 s[12:13], 0
	v_mov_b32_e32 v1, 0
	s_branch .LBB0_598

; DI unsigned xb_ld(unsigned* p) { return __hip_atomic_load(p, __ATOMIC_RELAXED, __HIP_MEMORY_SCOPE_AGENT); }
; DI unsigned xb_add(unsigned* p, unsigned v) { return __hip_atomic_fetch_add(p, v, __ATOMIC_RELAXED, __HIP_MEMORY_SCOPE_AGENT); }
; #define XB_SPIN(cond, bar) do { unsigned _sp = 0; while (cond) { __builtin_amdgcn_s_sleep(1); \
;     if ((++_sp & 255u) == 0u) { if (xb_ld(&(bar)[XB_TMO])) break; if (_sp > XB_SPIN_CAP) { atomicAdd(&(bar)[XB_TMO], 1u); break; } } } } while (0)
; DI void xcd_barrier(const XcdBarrier& b) {
;     ...
;         const unsigned old = xb_add(&bar[XB_XSUB(b.x)], 1u);
;         const unsigned gen = old / nloc;
;         if (old + 1u == (gen + 1u) * nloc) {
;             __builtin_amdgcn_fence(__ATOMIC_RELEASE, "agent");
;             asm volatile("s_waitcnt vmcnt(0)" ::: "memory");
;             const unsigned og = xb_add(&bar[XB_TOP], 1u);
;             const unsigned tg = og / nx;
;             if (og + 1u == (tg + 1u) * nx) xb_add(&bar[XB_TOPGEN], 1u);
;             else XB_SPIN(xb_ld(&bar[XB_TOPGEN]) == tg, bar);
;             __builtin_amdgcn_fence(__ATOMIC_ACQUIRE, "agent");
;             xb_add(&bar[XB_XGEN(b.x)], 1u);
;             asm volatile("s_waitcnt vmcnt(0)" ::: "memory");
;         } else {
;             XB_SPIN(xb_ld(&bar[XB_XGEN(b.x)]) == gen, bar);
;             __builtin_amdgcn_fence(__ATOMIC_ACQUIRE, "agent");
;             asm volatile("s_waitcnt vmcnt(0)" ::: "memory");
;         }
.LBB0_925:
	v_readlane_b32 s2, v238, 14
	s_lshl_b32 s2, s2, 8
	v_readlane_b32 s4, v238, 12
	v_readlane_b32 s5, v238, 13
	s_add_u32 s2, s4, s2
	s_addc_u32 s3, s5, 0
	v_mov_b32_e32 v1, 0x1000
	v_mov_b32_e32 v3, 1
	global_atomic_add v3, v1, v3, s[2:3] offset:1024 sc0
	v_cvt_f32_u32_e32 v1, v2
	v_sub_u32_e32 v4, 0, v2
	v_rcp_iflag_f32_e32 v1, v1
	s_nop 0
	v_mul_f32_e32 v1, 0x4f7ffffe, v1
	v_cvt_u32_f32_e32 v1, v1
	v_mul_lo_u32 v4, v4, v1
	v_mul_hi_u32 v4, v1, v4
	v_add_u32_e32 v1, v1, v4
	s_waitcnt vmcnt(0)
	v_mul_hi_u32 v1, v3, v1
	v_mul_lo_u32 v4, v1, v2
	v_sub_u32_e32 v4, v3, v4
	v_add_u32_e32 v5, 1, v1
	v_cmp_ge_u32_e32 vcc, v4, v2
	v_add_u32_e32 v3, 1, v3
	s_nop 0
	v_cndmask_b32_e32 v1, v1, v5, vcc
	v_sub_u32_e32 v5, v4, v2
	v_cndmask_b32_e32 v4, v4, v5, vcc
	v_add_u32_e32 v5, 1, v1
	v_cmp_ge_u32_e32 vcc, v4, v2
	s_nop 1
	v_cndmask_b32_e32 v1, v1, v5, vcc
	v_mul_lo_u32 v4, v2, v1
	v_add_u32_e32 v2, v4, v2
	v_cmp_ne_u32_e32 vcc, v3, v2
	s_and_saveexec_b64 s[4:5], vcc
	s_xor_b64 s[4:5], exec, s[4:5]
	s_cbranch_execz .LBB0_939
	s_waitcnt lgkmcnt(0)
	v_mov_b32_e32 v0, 0x4000
	global_load_dword v0, v0, s[88:89] offset:1280 sc1
	s_add_u32 s10, s88, 0x4500
	s_addc_u32 s11, s89, 0
	s_waitcnt vmcnt(0)
	v_cmp_eq_u32_e32 vcc, v0, v1
	s_and_saveexec_b64 s[6:7], vcc
	s_cbranch_execz .LBB0_938
	s_add_u32 s8, s88, 0x1200
	s_addc_u32 s9, s89, 0
	s_mov_b32 s22, 1
	s_mov_b64 s[12:13], 0
	v_mov_b32_e32 v0, 0
	s_branch .LBB0_929
